# MLA loop pipelined + gla_scan rewritten: chunk loads of a 16-step batch all in flight (double-buffered) instead of one round trip per step; numerics unchanged
# speedup vs baseline: 1.0275x; 1.0144x over previous
; __device__ __forceinline__ unsigned f2bf(float f) { unsigned u = __float_as_uint(f); return (u + 0x7fffu + ((u >> 16) & 1u)) >> 16; }
; __device__ __forceinline__ float bf2f(bf16_t h) { return __uint_as_float(((unsigned)h) << 16); }
; __device__ __forceinline__ void gla_scan(unsigned char* ws, int bid, int tid, int G) {
;     bf16_t* ST = (bf16_t*)(ws + O_ST); const float* GD = (const float*)(ws + O_GD);
;     for (int gidx = bid * NTHR + tid; gidx < 16 * 8192; gidx += G * NTHR) {
;         const int seq = gidx >> 13, idx = gidx & 8191, d = idx & 63, dir = seq & 1;
;         float s = 0.f;
;         for (int k0 = 0; k0 < 132; k0 += 33) {
;             float uv[33], dv[33];
; #pragma unroll
;             for (int u = 0; u < 33; ++u) { const int c = gla_ord(dir, k0 + u); uv[u] = bf2f(ST[(size_t)(seq * 132 + c) * 8192 + idx]); dv[u] = GD[(size_t)(seq * 132 + c) * 64 + d]; }
; #pragma unroll
;             for (int u = 0; u < 33; ++u) { const int c = gla_ord(dir, k0 + u); ST[(size_t)(seq * 132 + c) * 8192 + idx] = (bf16_t)f2bf(s); s = dv[u] * s + uv[u]; }
.LBB0_396:
	s_andn2_b64 vcc, exec, s[0:1]
	s_cbranch_vccnz .LBB0_506
	v_readlane_b32 s17, v254, 38
	s_mov_b32 s0, 0x20000
	s_nop 0
	v_lshl_add_u32 v37, s17, 9, v200
	v_cmp_gt_i32_e32 vcc, s0, v37
	s_and_saveexec_b64 s[2:3], vcc
	s_mov_b32 s16, 0x1ffff
	s_cbranch_execz .LBB0_402
	v_and_b32_e32 v0, 0x1fff, v37
	v_lshlrev_b32_e32 v0, 1, v0
	v_lshlrev_b32_e32 v1, 2, v202
	s_lshr_b32 s0, s17, 4
	s_and_b32 s1, s0, 1
	s_mul_i32 s0, s0, 0x84
	s_lshl_b32 s13, s0, 14
	s_add_u32 s10, s20, s13
	s_addc_u32 s11, s21, 0
	s_lshl_b32 s13, s0, 8
	s_add_u32 s14, s4, 0x3c0000
	s_addc_u32 s15, s5, 0
	s_add_u32 s14, s14, s13
	s_addc_u32 s15, s15, 0
	s_cmp_eq_u32 s1, 0
	s_movk_i32 s0, 0x4000
	s_cselect_b32 s0, s0, 0xffffc000
	s_movk_i32 s1, 0x100
	s_cselect_b32 s1, s1, 0xffffff00
	s_cselect_b32 s13, 0, 3
	s_cselect_b32 s16, 4, 0x83
	v_mov_b32_e32 v2, 0
	s_lshl_b32 s13, s13, 8
	v_add_u32_e32 v38, s13, v1
	v_mov_b32_e32 v39, v1
	v_mov_b32_e32 v1, v38
	s_lshl_b32 s13, s13, 6
	v_add_u32_e32 v4, s13, v0
	global_load_ushort v20, v4, s[10:11]
	global_load_dword v48, v1, s[14:15]
	v_add_u32_e32 v1, s1, v1
	v_add_u32_e32 v5, s0, v4
	global_load_ushort v21, v5, s[10:11]
	global_load_dword v49, v1, s[14:15]
	v_add_u32_e32 v1, s1, v1
	v_add_u32_e32 v6, s0, v5
	global_load_ushort v22, v6, s[10:11]
	global_load_dword v50, v1, s[14:15]
	v_add_u32_e32 v1, s1, v1
	v_add_u32_e32 v7, s0, v6
	global_load_ushort v23, v7, s[10:11]
	global_load_dword v51, v1, s[14:15]
	v_add_u32_e32 v1, s1, v1
	s_waitcnt vmcnt(6)
	v_bfe_u32 v3, v2, 16, 1
	v_add3_u32 v3, v2, v3, s86
	global_store_short_d16_hi v4, v3, s[10:11]
	v_lshlrev_b32_e32 v20, 16, v20
	v_fmac_f32_e32 v20, v48, v2
	s_waitcnt vmcnt(5)
	v_bfe_u32 v3, v20, 16, 1
	v_add3_u32 v3, v20, v3, s86
	global_store_short_d16_hi v5, v3, s[10:11]
	v_lshlrev_b32_e32 v21, 16, v21
	v_fmac_f32_e32 v21, v49, v20
	s_waitcnt vmcnt(4)
	v_bfe_u32 v3, v21, 16, 1
	v_add3_u32 v3, v21, v3, s86
	global_store_short_d16_hi v6, v3, s[10:11]
	v_lshlrev_b32_e32 v22, 16, v22
	v_fmac_f32_e32 v22, v50, v21
	s_waitcnt vmcnt(3)
	v_bfe_u32 v3, v22, 16, 1
	v_add3_u32 v3, v22, v3, s86
	global_store_short_d16_hi v7, v3, s[10:11]
	v_lshlrev_b32_e32 v23, 16, v23
	v_fmac_f32_e32 v23, v51, v22
	v_mov_b32_e32 v2, v23
	s_lshl_b32 s13, s16, 8
	v_add_u32_e32 v1, s13, v39
	s_lshl_b32 s13, s16, 14
	v_add_u32_e32 v4, s13, v0
	global_load_ushort v20, v4, s[10:11]
	global_load_dword v48, v1, s[14:15]
	v_add_u32_e32 v1, s1, v1
	v_add_u32_e32 v5, s0, v4
	global_load_ushort v21, v5, s[10:11]
	global_load_dword v49, v1, s[14:15]
	v_add_u32_e32 v1, s1, v1
	v_add_u32_e32 v6, s0, v5
	global_load_ushort v22, v6, s[10:11]
	global_load_dword v50, v1, s[14:15]
	v_add_u32_e32 v1, s1, v1
	v_add_u32_e32 v7, s0, v6
	global_load_ushort v23, v7, s[10:11]
	global_load_dword v51, v1, s[14:15]
	v_add_u32_e32 v1, s1, v1
	v_add_u32_e32 v8, s0, v7
	global_load_ushort v24, v8, s[10:11]
	global_load_dword v52, v1, s[14:15]
	v_add_u32_e32 v1, s1, v1
	v_add_u32_e32 v9, s0, v8
	global_load_ushort v25, v9, s[10:11]
	global_load_dword v53, v1, s[14:15]
	v_add_u32_e32 v1, s1, v1
	v_add_u32_e32 v10, s0, v9
	global_load_ushort v26, v10, s[10:11]
	global_load_dword v54, v1, s[14:15]
	v_add_u32_e32 v1, s1, v1
	v_add_u32_e32 v11, s0, v10
	global_load_ushort v27, v11, s[10:11]
	global_load_dword v55, v1, s[14:15]
	v_add_u32_e32 v1, s1, v1
	v_add_u32_e32 v12, s0, v11
	global_load_ushort v28, v12, s[10:11]
	global_load_dword v56, v1, s[14:15]
	v_add_u32_e32 v1, s1, v1
	v_add_u32_e32 v13, s0, v12
	global_load_ushort v29, v13, s[10:11]
	global_load_dword v57, v1, s[14:15]
	v_add_u32_e32 v1, s1, v1
	v_add_u32_e32 v14, s0, v13
	global_load_ushort v30, v14, s[10:11]
	global_load_dword v58, v1, s[14:15]
	v_add_u32_e32 v1, s1, v1
	v_add_u32_e32 v15, s0, v14
	global_load_ushort v31, v15, s[10:11]
	global_load_dword v59, v1, s[14:15]
	v_add_u32_e32 v1, s1, v1
	v_add_u32_e32 v16, s0, v15
	global_load_ushort v32, v16, s[10:11]
	global_load_dword v60, v1, s[14:15]
	v_add_u32_e32 v1, s1, v1
	v_add_u32_e32 v17, s0, v16
	global_load_ushort v33, v17, s[10:11]
	global_load_dword v61, v1, s[14:15]
	v_add_u32_e32 v1, s1, v1
	v_add_u32_e32 v18, s0, v17
	global_load_ushort v34, v18, s[10:11]
	global_load_dword v62, v1, s[14:15]
	v_add_u32_e32 v1, s1, v1
	v_add_u32_e32 v19, s0, v18
	global_load_ushort v35, v19, s[10:11]
	global_load_dword v63, v1, s[14:15]
	v_add_u32_e32 v1, s1, v1
	v_add_u32_e32 v38, s0, v19
	s_mov_b32 s13, 3
; __device__ __forceinline__ unsigned f2bf(float f) { unsigned u = __float_as_uint(f); return (u + 0x7fffu + ((u >> 16) & 1u)) >> 16; }
; __device__ __forceinline__ float bf2f(bf16_t h) { return __uint_as_float(((unsigned)h) << 16); }
; __device__ __forceinline__ void gla_scan(unsigned char* ws, int bid, int tid, int G) {
;     ...
;         for (int k0 = 0; k0 < 132; k0 += 33) {
;             float uv[33], dv[33];
; #pragma unroll
;             for (int u = 0; u < 33; ++u) { const int c = gla_ord(dir, k0 + u); uv[u] = bf2f(ST[(size_t)(seq * 132 + c) * 8192 + idx]); dv[u] = GD[(size_t)(seq * 132 + c) * 64 + d]; }
; #pragma unroll
;             for (int u = 0; u < 33; ++u) { const int c = gla_ord(dir, k0 + u); ST[(size_t)(seq * 132 + c) * 8192 + idx] = (bf16_t)f2bf(s); s = dv[u] * s + uv[u]; }
;         }
.Lscan_loop:
	v_mov_b32_e32 v64, v38
	global_load_ushort v80, v64, s[10:11]
	global_load_dword v96, v1, s[14:15]
	v_add_u32_e32 v1, s1, v1
	v_add_u32_e32 v65, s0, v64
	global_load_ushort v81, v65, s[10:11]
	global_load_dword v97, v1, s[14:15]
	v_add_u32_e32 v1, s1, v1
	v_add_u32_e32 v66, s0, v65
	global_load_ushort v82, v66, s[10:11]
	global_load_dword v98, v1, s[14:15]
	v_add_u32_e32 v1, s1, v1
	v_add_u32_e32 v67, s0, v66
	global_load_ushort v83, v67, s[10:11]
	global_load_dword v99, v1, s[14:15]
	v_add_u32_e32 v1, s1, v1
	v_add_u32_e32 v68, s0, v67
	global_load_ushort v84, v68, s[10:11]
	global_load_dword v100, v1, s[14:15]
	v_add_u32_e32 v1, s1, v1
	v_add_u32_e32 v69, s0, v68
	global_load_ushort v85, v69, s[10:11]
	global_load_dword v101, v1, s[14:15]
	v_add_u32_e32 v1, s1, v1
	v_add_u32_e32 v70, s0, v69
	global_load_ushort v86, v70, s[10:11]
	global_load_dword v102, v1, s[14:15]
	v_add_u32_e32 v1, s1, v1
	v_add_u32_e32 v71, s0, v70
	global_load_ushort v87, v71, s[10:11]
	global_load_dword v103, v1, s[14:15]
	v_add_u32_e32 v1, s1, v1
	v_add_u32_e32 v72, s0, v71
	global_load_ushort v88, v72, s[10:11]
	global_load_dword v104, v1, s[14:15]
	v_add_u32_e32 v1, s1, v1
	v_add_u32_e32 v73, s0, v72
	global_load_ushort v89, v73, s[10:11]
	global_load_dword v105, v1, s[14:15]
	v_add_u32_e32 v1, s1, v1
	v_add_u32_e32 v74, s0, v73
	global_load_ushort v90, v74, s[10:11]
	global_load_dword v106, v1, s[14:15]
	v_add_u32_e32 v1, s1, v1
	v_add_u32_e32 v75, s0, v74
	global_load_ushort v91, v75, s[10:11]
	global_load_dword v107, v1, s[14:15]
	v_add_u32_e32 v1, s1, v1
	v_add_u32_e32 v76, s0, v75
	global_load_ushort v92, v76, s[10:11]
	global_load_dword v108, v1, s[14:15]
	v_add_u32_e32 v1, s1, v1
	v_add_u32_e32 v77, s0, v76
	global_load_ushort v93, v77, s[10:11]
	global_load_dword v109, v1, s[14:15]
	v_add_u32_e32 v1, s1, v1
	v_add_u32_e32 v78, s0, v77
	global_load_ushort v94, v78, s[10:11]
	global_load_dword v110, v1, s[14:15]
	v_add_u32_e32 v1, s1, v1
	v_add_u32_e32 v79, s0, v78
	global_load_ushort v95, v79, s[10:11]
	global_load_dword v111, v1, s[14:15]
	v_add_u32_e32 v1, s1, v1
	v_add_u32_e32 v38, s0, v79
	s_waitcnt vmcnt(62)
	v_bfe_u32 v3, v2, 16, 1
	v_add3_u32 v3, v2, v3, s86
	global_store_short_d16_hi v4, v3, s[10:11]
	v_lshlrev_b32_e32 v20, 16, v20
	v_fmac_f32_e32 v20, v48, v2
	s_waitcnt vmcnt(61)
	v_bfe_u32 v3, v20, 16, 1
	v_add3_u32 v3, v20, v3, s86
	global_store_short_d16_hi v5, v3, s[10:11]
	v_lshlrev_b32_e32 v21, 16, v21
	v_fmac_f32_e32 v21, v49, v20
	s_waitcnt vmcnt(60)
	v_bfe_u32 v3, v21, 16, 1
	v_add3_u32 v3, v21, v3, s86
	global_store_short_d16_hi v6, v3, s[10:11]
	v_lshlrev_b32_e32 v22, 16, v22
	v_fmac_f32_e32 v22, v50, v21
	s_waitcnt vmcnt(59)
	v_bfe_u32 v3, v22, 16, 1
	v_add3_u32 v3, v22, v3, s86
	global_store_short_d16_hi v7, v3, s[10:11]
	v_lshlrev_b32_e32 v23, 16, v23
	v_fmac_f32_e32 v23, v51, v22
	s_waitcnt vmcnt(58)
	v_bfe_u32 v3, v23, 16, 1
	v_add3_u32 v3, v23, v3, s86
	global_store_short_d16_hi v8, v3, s[10:11]
	v_lshlrev_b32_e32 v24, 16, v24
	v_fmac_f32_e32 v24, v52, v23
	s_waitcnt vmcnt(57)
	v_bfe_u32 v3, v24, 16, 1
	v_add3_u32 v3, v24, v3, s86
	global_store_short_d16_hi v9, v3, s[10:11]
	v_lshlrev_b32_e32 v25, 16, v25
	v_fmac_f32_e32 v25, v53, v24
	s_waitcnt vmcnt(56)
	v_bfe_u32 v3, v25, 16, 1
	v_add3_u32 v3, v25, v3, s86
	global_store_short_d16_hi v10, v3, s[10:11]
	v_lshlrev_b32_e32 v26, 16, v26
	v_fmac_f32_e32 v26, v54, v25
	s_waitcnt vmcnt(55)
	v_bfe_u32 v3, v26, 16, 1
	v_add3_u32 v3, v26, v3, s86
	global_store_short_d16_hi v11, v3, s[10:11]
	v_lshlrev_b32_e32 v27, 16, v27
	v_fmac_f32_e32 v27, v55, v26
	s_waitcnt vmcnt(54)
	v_bfe_u32 v3, v27, 16, 1
	v_add3_u32 v3, v27, v3, s86
	global_store_short_d16_hi v12, v3, s[10:11]
	v_lshlrev_b32_e32 v28, 16, v28
	v_fmac_f32_e32 v28, v56, v27
	s_waitcnt vmcnt(53)
	v_bfe_u32 v3, v28, 16, 1
	v_add3_u32 v3, v28, v3, s86
	global_store_short_d16_hi v13, v3, s[10:11]
	v_lshlrev_b32_e32 v29, 16, v29
	v_fmac_f32_e32 v29, v57, v28
	s_waitcnt vmcnt(52)
	v_bfe_u32 v3, v29, 16, 1
	v_add3_u32 v3, v29, v3, s86
	global_store_short_d16_hi v14, v3, s[10:11]
	v_lshlrev_b32_e32 v30, 16, v30
	v_fmac_f32_e32 v30, v58, v29
	s_waitcnt vmcnt(51)
	v_bfe_u32 v3, v30, 16, 1
	v_add3_u32 v3, v30, v3, s86
	global_store_short_d16_hi v15, v3, s[10:11]
	v_lshlrev_b32_e32 v31, 16, v31
	v_fmac_f32_e32 v31, v59, v30
	s_waitcnt vmcnt(50)
	v_bfe_u32 v3, v31, 16, 1
	v_add3_u32 v3, v31, v3, s86
	global_store_short_d16_hi v16, v3, s[10:11]
	v_lshlrev_b32_e32 v32, 16, v32
	v_fmac_f32_e32 v32, v60, v31
	s_waitcnt vmcnt(49)
	v_bfe_u32 v3, v32, 16, 1
	v_add3_u32 v3, v32, v3, s86
	global_store_short_d16_hi v17, v3, s[10:11]
	v_lshlrev_b32_e32 v33, 16, v33
	v_fmac_f32_e32 v33, v61, v32
	s_waitcnt vmcnt(48)
	v_bfe_u32 v3, v33, 16, 1
	v_add3_u32 v3, v33, v3, s86
	global_store_short_d16_hi v18, v3, s[10:11]
	v_lshlrev_b32_e32 v34, 16, v34
	v_fmac_f32_e32 v34, v62, v33
	s_waitcnt vmcnt(47)
; __device__ __forceinline__ unsigned f2bf(float f) { unsigned u = __float_as_uint(f); return (u + 0x7fffu + ((u >> 16) & 1u)) >> 16; }
; __device__ __forceinline__ float bf2f(bf16_t h) { return __uint_as_float(((unsigned)h) << 16); }
; __device__ __forceinline__ void gla_scan(unsigned char* ws, int bid, int tid, int G) {
;     ...
;         for (int k0 = 0; k0 < 132; k0 += 33) {
;             float uv[33], dv[33];
; #pragma unroll
;             for (int u = 0; u < 33; ++u) { const int c = gla_ord(dir, k0 + u); uv[u] = bf2f(ST[(size_t)(seq * 132 + c) * 8192 + idx]); dv[u] = GD[(size_t)(seq * 132 + c) * 64 + d]; }
; #pragma unroll
;             for (int u = 0; u < 33; ++u) { const int c = gla_ord(dir, k0 + u); ST[(size_t)(seq * 132 + c) * 8192 + idx] = (bf16_t)f2bf(s); s = dv[u] * s + uv[u]; }
;         }
	v_bfe_u32 v3, v34, 16, 1
	v_add3_u32 v3, v34, v3, s86
	global_store_short_d16_hi v19, v3, s[10:11]
	v_lshlrev_b32_e32 v35, 16, v35
	v_fmac_f32_e32 v35, v63, v34
	v_mov_b32_e32 v2, v35
	v_mov_b32_e32 v4, v38
	global_load_ushort v20, v4, s[10:11]
	global_load_dword v48, v1, s[14:15]
	v_add_u32_e32 v1, s1, v1
	v_add_u32_e32 v5, s0, v4
	global_load_ushort v21, v5, s[10:11]
	global_load_dword v49, v1, s[14:15]
	v_add_u32_e32 v1, s1, v1
	v_add_u32_e32 v6, s0, v5
	global_load_ushort v22, v6, s[10:11]
	global_load_dword v50, v1, s[14:15]
	v_add_u32_e32 v1, s1, v1
	v_add_u32_e32 v7, s0, v6
	global_load_ushort v23, v7, s[10:11]
	global_load_dword v51, v1, s[14:15]
	v_add_u32_e32 v1, s1, v1
	v_add_u32_e32 v8, s0, v7
	global_load_ushort v24, v8, s[10:11]
	global_load_dword v52, v1, s[14:15]
	v_add_u32_e32 v1, s1, v1
	v_add_u32_e32 v9, s0, v8
	global_load_ushort v25, v9, s[10:11]
	global_load_dword v53, v1, s[14:15]
	v_add_u32_e32 v1, s1, v1
	v_add_u32_e32 v10, s0, v9
	global_load_ushort v26, v10, s[10:11]
	global_load_dword v54, v1, s[14:15]
	v_add_u32_e32 v1, s1, v1
	v_add_u32_e32 v11, s0, v10
	global_load_ushort v27, v11, s[10:11]
	global_load_dword v55, v1, s[14:15]
	v_add_u32_e32 v1, s1, v1
	v_add_u32_e32 v12, s0, v11
	global_load_ushort v28, v12, s[10:11]
	global_load_dword v56, v1, s[14:15]
	v_add_u32_e32 v1, s1, v1
	v_add_u32_e32 v13, s0, v12
	global_load_ushort v29, v13, s[10:11]
	global_load_dword v57, v1, s[14:15]
	v_add_u32_e32 v1, s1, v1
	v_add_u32_e32 v14, s0, v13
	global_load_ushort v30, v14, s[10:11]
	global_load_dword v58, v1, s[14:15]
	v_add_u32_e32 v1, s1, v1
	v_add_u32_e32 v15, s0, v14
	global_load_ushort v31, v15, s[10:11]
	global_load_dword v59, v1, s[14:15]
	v_add_u32_e32 v1, s1, v1
	v_add_u32_e32 v16, s0, v15
	global_load_ushort v32, v16, s[10:11]
	global_load_dword v60, v1, s[14:15]
	v_add_u32_e32 v1, s1, v1
	v_add_u32_e32 v17, s0, v16
	global_load_ushort v33, v17, s[10:11]
	global_load_dword v61, v1, s[14:15]
	v_add_u32_e32 v1, s1, v1
	v_add_u32_e32 v18, s0, v17
	global_load_ushort v34, v18, s[10:11]
	global_load_dword v62, v1, s[14:15]
	v_add_u32_e32 v1, s1, v1
	v_add_u32_e32 v19, s0, v18
	global_load_ushort v35, v19, s[10:11]
	global_load_dword v63, v1, s[14:15]
	v_add_u32_e32 v1, s1, v1
	v_add_u32_e32 v38, s0, v19
	s_waitcnt vmcnt(62)
	v_bfe_u32 v3, v2, 16, 1
	v_add3_u32 v3, v2, v3, s86
	global_store_short_d16_hi v64, v3, s[10:11]
	v_lshlrev_b32_e32 v80, 16, v80
	v_fmac_f32_e32 v80, v96, v2
	s_waitcnt vmcnt(61)
	v_bfe_u32 v3, v80, 16, 1
	v_add3_u32 v3, v80, v3, s86
	global_store_short_d16_hi v65, v3, s[10:11]
	v_lshlrev_b32_e32 v81, 16, v81
	v_fmac_f32_e32 v81, v97, v80
	s_waitcnt vmcnt(60)
	v_bfe_u32 v3, v81, 16, 1
	v_add3_u32 v3, v81, v3, s86
	global_store_short_d16_hi v66, v3, s[10:11]
	v_lshlrev_b32_e32 v82, 16, v82
	v_fmac_f32_e32 v82, v98, v81
	s_waitcnt vmcnt(59)
	v_bfe_u32 v3, v82, 16, 1
	v_add3_u32 v3, v82, v3, s86
	global_store_short_d16_hi v67, v3, s[10:11]
	v_lshlrev_b32_e32 v83, 16, v83
	v_fmac_f32_e32 v83, v99, v82
	s_waitcnt vmcnt(58)
	v_bfe_u32 v3, v83, 16, 1
	v_add3_u32 v3, v83, v3, s86
	global_store_short_d16_hi v68, v3, s[10:11]
	v_lshlrev_b32_e32 v84, 16, v84
	v_fmac_f32_e32 v84, v100, v83
	s_waitcnt vmcnt(57)
	v_bfe_u32 v3, v84, 16, 1
	v_add3_u32 v3, v84, v3, s86
	global_store_short_d16_hi v69, v3, s[10:11]
	v_lshlrev_b32_e32 v85, 16, v85
	v_fmac_f32_e32 v85, v101, v84
	s_waitcnt vmcnt(56)
	v_bfe_u32 v3, v85, 16, 1
	v_add3_u32 v3, v85, v3, s86
	global_store_short_d16_hi v70, v3, s[10:11]
	v_lshlrev_b32_e32 v86, 16, v86
	v_fmac_f32_e32 v86, v102, v85
	s_waitcnt vmcnt(55)
	v_bfe_u32 v3, v86, 16, 1
	v_add3_u32 v3, v86, v3, s86
	global_store_short_d16_hi v71, v3, s[10:11]
	v_lshlrev_b32_e32 v87, 16, v87
	v_fmac_f32_e32 v87, v103, v86
	s_waitcnt vmcnt(54)
	v_bfe_u32 v3, v87, 16, 1
	v_add3_u32 v3, v87, v3, s86
	global_store_short_d16_hi v72, v3, s[10:11]
	v_lshlrev_b32_e32 v88, 16, v88
	v_fmac_f32_e32 v88, v104, v87
	s_waitcnt vmcnt(53)
	v_bfe_u32 v3, v88, 16, 1
	v_add3_u32 v3, v88, v3, s86
	global_store_short_d16_hi v73, v3, s[10:11]
	v_lshlrev_b32_e32 v89, 16, v89
	v_fmac_f32_e32 v89, v105, v88
	s_waitcnt vmcnt(52)
	v_bfe_u32 v3, v89, 16, 1
	v_add3_u32 v3, v89, v3, s86
	global_store_short_d16_hi v74, v3, s[10:11]
	v_lshlrev_b32_e32 v90, 16, v90
	v_fmac_f32_e32 v90, v106, v89
	s_waitcnt vmcnt(51)
	v_bfe_u32 v3, v90, 16, 1
	v_add3_u32 v3, v90, v3, s86
	global_store_short_d16_hi v75, v3, s[10:11]
	v_lshlrev_b32_e32 v91, 16, v91
	v_fmac_f32_e32 v91, v107, v90
	s_waitcnt vmcnt(50)
	v_bfe_u32 v3, v91, 16, 1
	v_add3_u32 v3, v91, v3, s86
	global_store_short_d16_hi v76, v3, s[10:11]
	v_lshlrev_b32_e32 v92, 16, v92
	v_fmac_f32_e32 v92, v108, v91
	s_waitcnt vmcnt(49)
	v_bfe_u32 v3, v92, 16, 1
	v_add3_u32 v3, v92, v3, s86
	global_store_short_d16_hi v77, v3, s[10:11]
	v_lshlrev_b32_e32 v93, 16, v93
	v_fmac_f32_e32 v93, v109, v92
	s_waitcnt vmcnt(48)
	v_bfe_u32 v3, v93, 16, 1
	v_add3_u32 v3, v93, v3, s86
	global_store_short_d16_hi v78, v3, s[10:11]
	v_lshlrev_b32_e32 v94, 16, v94
	v_fmac_f32_e32 v94, v110, v93
	s_waitcnt vmcnt(47)
	v_bfe_u32 v3, v94, 16, 1
	v_add3_u32 v3, v94, v3, s86
	global_store_short_d16_hi v79, v3, s[10:11]
	v_lshlrev_b32_e32 v95, 16, v95
	v_fmac_f32_e32 v95, v111, v94
	v_mov_b32_e32 v2, v95
	s_sub_i32 s13, s13, 1
	s_cmp_lg_u32 s13, 0
	s_cbranch_scc1 .Lscan_loop
; __device__ __forceinline__ unsigned f2bf(float f) { unsigned u = __float_as_uint(f); return (u + 0x7fffu + ((u >> 16) & 1u)) >> 16; }
; __device__ __forceinline__ float bf2f(bf16_t h) { return __uint_as_float(((unsigned)h) << 16); }
; __device__ __forceinline__ void gla_scan(unsigned char* ws, int bid, int tid, int G) {
;     ...
;         for (int k0 = 0; k0 < 132; k0 += 33) {
;             float uv[33], dv[33];
; #pragma unroll
;             for (int u = 0; u < 33; ++u) { const int c = gla_ord(dir, k0 + u); uv[u] = bf2f(ST[(size_t)(seq * 132 + c) * 8192 + idx]); dv[u] = GD[(size_t)(seq * 132 + c) * 64 + d]; }
; #pragma unroll
;             for (int u = 0; u < 33; ++u) { const int c = gla_ord(dir, k0 + u); ST[(size_t)(seq * 132 + c) * 8192 + idx] = (bf16_t)f2bf(s); s = dv[u] * s + uv[u]; }
;         }
	v_mov_b32_e32 v64, v38
	global_load_ushort v80, v64, s[10:11]
	global_load_dword v96, v1, s[14:15]
	v_add_u32_e32 v1, s1, v1
	v_add_u32_e32 v65, s0, v64
	global_load_ushort v81, v65, s[10:11]
	global_load_dword v97, v1, s[14:15]
	v_add_u32_e32 v1, s1, v1
	v_add_u32_e32 v66, s0, v65
	global_load_ushort v82, v66, s[10:11]
	global_load_dword v98, v1, s[14:15]
	v_add_u32_e32 v1, s1, v1
	v_add_u32_e32 v67, s0, v66
	global_load_ushort v83, v67, s[10:11]
	global_load_dword v99, v1, s[14:15]
	v_add_u32_e32 v1, s1, v1
	v_add_u32_e32 v68, s0, v67
	global_load_ushort v84, v68, s[10:11]
	global_load_dword v100, v1, s[14:15]
	v_add_u32_e32 v1, s1, v1
	v_add_u32_e32 v69, s0, v68
	global_load_ushort v85, v69, s[10:11]
	global_load_dword v101, v1, s[14:15]
	v_add_u32_e32 v1, s1, v1
	v_add_u32_e32 v70, s0, v69
	global_load_ushort v86, v70, s[10:11]
	global_load_dword v102, v1, s[14:15]
	v_add_u32_e32 v1, s1, v1
	v_add_u32_e32 v71, s0, v70
	global_load_ushort v87, v71, s[10:11]
	global_load_dword v103, v1, s[14:15]
	v_add_u32_e32 v1, s1, v1
	v_add_u32_e32 v72, s0, v71
	global_load_ushort v88, v72, s[10:11]
	global_load_dword v104, v1, s[14:15]
	v_add_u32_e32 v1, s1, v1
	v_add_u32_e32 v73, s0, v72
	global_load_ushort v89, v73, s[10:11]
	global_load_dword v105, v1, s[14:15]
	v_add_u32_e32 v1, s1, v1
	v_add_u32_e32 v74, s0, v73
	global_load_ushort v90, v74, s[10:11]
	global_load_dword v106, v1, s[14:15]
	v_add_u32_e32 v1, s1, v1
	v_add_u32_e32 v75, s0, v74
	global_load_ushort v91, v75, s[10:11]
	global_load_dword v107, v1, s[14:15]
	v_add_u32_e32 v1, s1, v1
	v_add_u32_e32 v76, s0, v75
	global_load_ushort v92, v76, s[10:11]
	global_load_dword v108, v1, s[14:15]
	v_add_u32_e32 v1, s1, v1
	v_add_u32_e32 v77, s0, v76
	global_load_ushort v93, v77, s[10:11]
	global_load_dword v109, v1, s[14:15]
	v_add_u32_e32 v1, s1, v1
	v_add_u32_e32 v78, s0, v77
	global_load_ushort v94, v78, s[10:11]
	global_load_dword v110, v1, s[14:15]
	v_add_u32_e32 v1, s1, v1
	v_add_u32_e32 v79, s0, v78
	global_load_ushort v95, v79, s[10:11]
	global_load_dword v111, v1, s[14:15]
	v_add_u32_e32 v1, s1, v1
	s_waitcnt vmcnt(62)
	v_bfe_u32 v3, v2, 16, 1
	v_add3_u32 v3, v2, v3, s86
	global_store_short_d16_hi v4, v3, s[10:11]
	v_lshlrev_b32_e32 v20, 16, v20
	v_fmac_f32_e32 v20, v48, v2
	s_waitcnt vmcnt(61)
	v_bfe_u32 v3, v20, 16, 1
	v_add3_u32 v3, v20, v3, s86
	global_store_short_d16_hi v5, v3, s[10:11]
	v_lshlrev_b32_e32 v21, 16, v21
	v_fmac_f32_e32 v21, v49, v20
	s_waitcnt vmcnt(60)
	v_bfe_u32 v3, v21, 16, 1
	v_add3_u32 v3, v21, v3, s86
	global_store_short_d16_hi v6, v3, s[10:11]
	v_lshlrev_b32_e32 v22, 16, v22
	v_fmac_f32_e32 v22, v50, v21
	s_waitcnt vmcnt(59)
	v_bfe_u32 v3, v22, 16, 1
	v_add3_u32 v3, v22, v3, s86
	global_store_short_d16_hi v7, v3, s[10:11]
	v_lshlrev_b32_e32 v23, 16, v23
	v_fmac_f32_e32 v23, v51, v22
	s_waitcnt vmcnt(58)
	v_bfe_u32 v3, v23, 16, 1
	v_add3_u32 v3, v23, v3, s86
	global_store_short_d16_hi v8, v3, s[10:11]
	v_lshlrev_b32_e32 v24, 16, v24
	v_fmac_f32_e32 v24, v52, v23
	s_waitcnt vmcnt(57)
	v_bfe_u32 v3, v24, 16, 1
	v_add3_u32 v3, v24, v3, s86
	global_store_short_d16_hi v9, v3, s[10:11]
	v_lshlrev_b32_e32 v25, 16, v25
	v_fmac_f32_e32 v25, v53, v24
	s_waitcnt vmcnt(56)
	v_bfe_u32 v3, v25, 16, 1
	v_add3_u32 v3, v25, v3, s86
	global_store_short_d16_hi v10, v3, s[10:11]
	v_lshlrev_b32_e32 v26, 16, v26
	v_fmac_f32_e32 v26, v54, v25
	s_waitcnt vmcnt(55)
	v_bfe_u32 v3, v26, 16, 1
	v_add3_u32 v3, v26, v3, s86
	global_store_short_d16_hi v11, v3, s[10:11]
	v_lshlrev_b32_e32 v27, 16, v27
	v_fmac_f32_e32 v27, v55, v26
	s_waitcnt vmcnt(54)
	v_bfe_u32 v3, v27, 16, 1
	v_add3_u32 v3, v27, v3, s86
	global_store_short_d16_hi v12, v3, s[10:11]
	v_lshlrev_b32_e32 v28, 16, v28
	v_fmac_f32_e32 v28, v56, v27
	s_waitcnt vmcnt(53)
	v_bfe_u32 v3, v28, 16, 1
	v_add3_u32 v3, v28, v3, s86
	global_store_short_d16_hi v13, v3, s[10:11]
	v_lshlrev_b32_e32 v29, 16, v29
	v_fmac_f32_e32 v29, v57, v28
	s_waitcnt vmcnt(52)
; __device__ __forceinline__ unsigned f2bf(float f) { unsigned u = __float_as_uint(f); return (u + 0x7fffu + ((u >> 16) & 1u)) >> 16; }
; __device__ __forceinline__ float bf2f(bf16_t h) { return __uint_as_float(((unsigned)h) << 16); }
; __device__ __forceinline__ void gla_scan(unsigned char* ws, int bid, int tid, int G) {
;     ...
;         for (int k0 = 0; k0 < 132; k0 += 33) {
;             float uv[33], dv[33];
; #pragma unroll
;             for (int u = 0; u < 33; ++u) { const int c = gla_ord(dir, k0 + u); uv[u] = bf2f(ST[(size_t)(seq * 132 + c) * 8192 + idx]); dv[u] = GD[(size_t)(seq * 132 + c) * 64 + d]; }
; #pragma unroll
;             for (int u = 0; u < 33; ++u) { const int c = gla_ord(dir, k0 + u); ST[(size_t)(seq * 132 + c) * 8192 + idx] = (bf16_t)f2bf(s); s = dv[u] * s + uv[u]; }
;         }
	v_bfe_u32 v3, v29, 16, 1
	v_add3_u32 v3, v29, v3, s86
	global_store_short_d16_hi v14, v3, s[10:11]
	v_lshlrev_b32_e32 v30, 16, v30
	v_fmac_f32_e32 v30, v58, v29
	s_waitcnt vmcnt(51)
	v_bfe_u32 v3, v30, 16, 1
	v_add3_u32 v3, v30, v3, s86
	global_store_short_d16_hi v15, v3, s[10:11]
	v_lshlrev_b32_e32 v31, 16, v31
	v_fmac_f32_e32 v31, v59, v30
	s_waitcnt vmcnt(50)
	v_bfe_u32 v3, v31, 16, 1
	v_add3_u32 v3, v31, v3, s86
	global_store_short_d16_hi v16, v3, s[10:11]
	v_lshlrev_b32_e32 v32, 16, v32
	v_fmac_f32_e32 v32, v60, v31
	s_waitcnt vmcnt(49)
	v_bfe_u32 v3, v32, 16, 1
	v_add3_u32 v3, v32, v3, s86
	global_store_short_d16_hi v17, v3, s[10:11]
	v_lshlrev_b32_e32 v33, 16, v33
	v_fmac_f32_e32 v33, v61, v32
	s_waitcnt vmcnt(48)
	v_bfe_u32 v3, v33, 16, 1
	v_add3_u32 v3, v33, v3, s86
	global_store_short_d16_hi v18, v3, s[10:11]
	v_lshlrev_b32_e32 v34, 16, v34
	v_fmac_f32_e32 v34, v62, v33
	s_waitcnt vmcnt(47)
	v_bfe_u32 v3, v34, 16, 1
	v_add3_u32 v3, v34, v3, s86
	global_store_short_d16_hi v19, v3, s[10:11]
	v_lshlrev_b32_e32 v35, 16, v35
	v_fmac_f32_e32 v35, v63, v34
	v_mov_b32_e32 v2, v35
	s_waitcnt vmcnt(30)
	v_bfe_u32 v3, v2, 16, 1
	v_add3_u32 v3, v2, v3, s86
	global_store_short_d16_hi v64, v3, s[10:11]
	v_lshlrev_b32_e32 v80, 16, v80
	v_fmac_f32_e32 v80, v96, v2
	s_waitcnt vmcnt(29)
	v_bfe_u32 v3, v80, 16, 1
	v_add3_u32 v3, v80, v3, s86
	global_store_short_d16_hi v65, v3, s[10:11]
	v_lshlrev_b32_e32 v81, 16, v81
	v_fmac_f32_e32 v81, v97, v80
	s_waitcnt vmcnt(28)
	v_bfe_u32 v3, v81, 16, 1
	v_add3_u32 v3, v81, v3, s86
	global_store_short_d16_hi v66, v3, s[10:11]
	v_lshlrev_b32_e32 v82, 16, v82
	v_fmac_f32_e32 v82, v98, v81
	s_waitcnt vmcnt(27)
	v_bfe_u32 v3, v82, 16, 1
	v_add3_u32 v3, v82, v3, s86
	global_store_short_d16_hi v67, v3, s[10:11]
	v_lshlrev_b32_e32 v83, 16, v83
	v_fmac_f32_e32 v83, v99, v82
	s_waitcnt vmcnt(26)
	v_bfe_u32 v3, v83, 16, 1
	v_add3_u32 v3, v83, v3, s86
	global_store_short_d16_hi v68, v3, s[10:11]
	v_lshlrev_b32_e32 v84, 16, v84
	v_fmac_f32_e32 v84, v100, v83
	s_waitcnt vmcnt(25)
	v_bfe_u32 v3, v84, 16, 1
	v_add3_u32 v3, v84, v3, s86
	global_store_short_d16_hi v69, v3, s[10:11]
	v_lshlrev_b32_e32 v85, 16, v85
	v_fmac_f32_e32 v85, v101, v84
	s_waitcnt vmcnt(24)
	v_bfe_u32 v3, v85, 16, 1
	v_add3_u32 v3, v85, v3, s86
	global_store_short_d16_hi v70, v3, s[10:11]
	v_lshlrev_b32_e32 v86, 16, v86
	v_fmac_f32_e32 v86, v102, v85
	s_waitcnt vmcnt(23)
	v_bfe_u32 v3, v86, 16, 1
	v_add3_u32 v3, v86, v3, s86
	global_store_short_d16_hi v71, v3, s[10:11]
	v_lshlrev_b32_e32 v87, 16, v87
	v_fmac_f32_e32 v87, v103, v86
	s_waitcnt vmcnt(22)
	v_bfe_u32 v3, v87, 16, 1
	v_add3_u32 v3, v87, v3, s86
	global_store_short_d16_hi v72, v3, s[10:11]
	v_lshlrev_b32_e32 v88, 16, v88
	v_fmac_f32_e32 v88, v104, v87
	s_waitcnt vmcnt(21)
	v_bfe_u32 v3, v88, 16, 1
	v_add3_u32 v3, v88, v3, s86
	global_store_short_d16_hi v73, v3, s[10:11]
	v_lshlrev_b32_e32 v89, 16, v89
	v_fmac_f32_e32 v89, v105, v88
	s_waitcnt vmcnt(20)
	v_bfe_u32 v3, v89, 16, 1
	v_add3_u32 v3, v89, v3, s86
	global_store_short_d16_hi v74, v3, s[10:11]
	v_lshlrev_b32_e32 v90, 16, v90
	v_fmac_f32_e32 v90, v106, v89
	s_waitcnt vmcnt(19)
	v_bfe_u32 v3, v90, 16, 1
	v_add3_u32 v3, v90, v3, s86
	global_store_short_d16_hi v75, v3, s[10:11]
	v_lshlrev_b32_e32 v91, 16, v91
	v_fmac_f32_e32 v91, v107, v90
	s_waitcnt vmcnt(18)
	v_bfe_u32 v3, v91, 16, 1
	v_add3_u32 v3, v91, v3, s86
	global_store_short_d16_hi v76, v3, s[10:11]
	v_lshlrev_b32_e32 v92, 16, v92
	v_fmac_f32_e32 v92, v108, v91
	s_waitcnt vmcnt(17)
	v_bfe_u32 v3, v92, 16, 1
	v_add3_u32 v3, v92, v3, s86
	global_store_short_d16_hi v77, v3, s[10:11]
	v_lshlrev_b32_e32 v93, 16, v93
	v_fmac_f32_e32 v93, v109, v92
	s_waitcnt vmcnt(16)
	v_bfe_u32 v3, v93, 16, 1
	v_add3_u32 v3, v93, v3, s86
	global_store_short_d16_hi v78, v3, s[10:11]
	v_lshlrev_b32_e32 v94, 16, v94
	v_fmac_f32_e32 v94, v110, v93
	s_waitcnt vmcnt(15)
	v_bfe_u32 v3, v94, 16, 1
	v_add3_u32 v3, v94, v3, s86
	global_store_short_d16_hi v79, v3, s[10:11]
	v_lshlrev_b32_e32 v95, 16, v95
	v_fmac_f32_e32 v95, v111, v94
	v_mov_b32_e32 v2, v95
